# v33_seam
# baseline (speedup 1.0000x reference)
; DI unsigned pack2(float a, float b) { fl2_t v = {a, b}; bf2_t r = __builtin_convertvector(v, bf2_t); return __builtin_bit_cast(unsigned, r); }
; DI float bflo(unsigned u) { return __uint_as_float(u << 16); }
; DI float bfhi(unsigned u) { return __uint_as_float(u & 0xffff0000u); }
; DI float sigmoidf_(float x) { return __builtin_amdgcn_rcpf(1.f + __builtin_amdgcn_exp2f(-1.4426950408889634f * x)); }
; DI float fxc(const i64* p) { return (float)(*p) * FXC_INV; }
; DI float rl(float v, int srclane) { return __int_as_float(__builtin_amdgcn_readlane(__float_as_int(v), srclane)); }
; DI void epi_rows(const Params& p, int L, int ekind, const float* T, int rbase, int bcol) {
;     ...
;     default: {
;       const bool a = ekind == E_GATE_A;
;       const i64* st = ST_(L, 0); const int co = a ? CS_WGA : CS_WGB;
;       const size_t off0 = (size_t)(rbase + lr0) * 1024 + bcol + c4;
;       const u16* src = (const u16*)(R + (a ? R_MX : R_GT)) + off0; u16* Mx = (u16*)(R + R_MX) + off0;
;       f32x4 cs4, bw4;
;       for (int k = 0; k < 4; ++k) { cs4[k] = fxc(cs + co + bcol + c4 + k); bw4[k] = fxc(bw + co + bcol + c4 + k); }
;       RowStat rs_l = row_stat(st, myrow);
;       #pragma unroll 1
;       for (int ch = 0; ch < 2; ++ch) {
;         u32x2 sv[8], mv[8];
;         #pragma unroll
;         for (int i = 0; i < 8; ++i) {
;           sv[i] = ldg<u32x2>(src + (size_t)(ch * 8 + i) * 1024);
;           if (!a) mv[i] = ldg<u32x2>(Mx + (size_t)(ch * 8 + i) * 1024);
;         }
;         #pragma unroll
;         for (int i = 0; i < 8; ++i) {
;           const int ri = ch * 8 + i;
;           const float mu = rl(rs_l.mu, ri), rstd = rl(rs_l.rstd, ri);
;           f32x4 t = *(const f32x4*)(T + (lr0 + ri) * TSTR + c4);
;           float sf[4] = {bflo(sv[i][0]), bfhi(sv[i][0]), bflo(sv[i][1]), bfhi(sv[i][1])};
;           float v[4];
;           for (int k = 0; k < 4; ++k) v[k] = sigmoidf_(rstd * (t[k] - mu * cs4[k]) + bw4[k]) * sf[k];
;           if (!a) { v[0] += bflo(mv[i][0]); v[1] += bfhi(mv[i][0]); v[2] += bflo(mv[i][1]); v[3] += bfhi(mv[i][1]); }
;           u32x2 o; o[0] = pack2(v[0], v[1]); o[1] = pack2(v[2], v[3]);
;           stg<u32x2>(Mx + (size_t)ri * 1024, o);
;         }
.LBB0_1767:
	s_lshl_b32 s50, s6, 14
	v_lshl_add_u64 v[2:3], v[6:7], 0, s[50:51]
	global_load_dwordx2 v[48:49], v[2:3], off
	v_lshl_add_u64 v[50:51], v[8:9], 0, s[50:51]
	global_load_dwordx2 v[52:53], v[50:51], off
	global_load_dwordx2 v[32:33], v[2:3], off offset:2048
	global_load_dwordx2 v[30:31], v[50:51], off offset:2048
	s_or_b32 s10, s50, 0x1000
	s_mov_b32 s11, s51
	v_lshl_add_u64 v[2:3], v[6:7], 0, s[10:11]
	global_load_dwordx2 v[26:27], v[2:3], off
	v_lshl_add_u64 v[2:3], v[8:9], 0, s[10:11]
	global_load_dwordx2 v[28:29], v[2:3], off
	s_or_b32 s10, s50, 0x1800
	v_lshl_add_u64 v[2:3], v[6:7], 0, s[10:11]
	global_load_dwordx2 v[22:23], v[2:3], off
	v_lshl_add_u64 v[2:3], v[8:9], 0, s[10:11]
	s_or_b32 s10, s50, 0x2000
	global_load_dwordx2 v[24:25], v[2:3], off
	v_lshl_add_u64 v[2:3], v[6:7], 0, s[10:11]
	global_load_dwordx2 v[18:19], v[2:3], off
	v_lshl_add_u64 v[2:3], v[8:9], 0, s[10:11]
	s_or_b32 s10, s50, 0x2800
	global_load_dwordx2 v[20:21], v[2:3], off
	v_lshl_add_u64 v[2:3], v[6:7], 0, s[10:11]
	global_load_dwordx2 v[14:15], v[2:3], off
	v_lshl_add_u64 v[2:3], v[8:9], 0, s[10:11]
	s_or_b32 s10, s50, 0x3000
	global_load_dwordx2 v[16:17], v[2:3], off
	v_lshl_add_u64 v[2:3], v[6:7], 0, s[10:11]
	s_lshl_b32 s7, s6, 3
	global_load_dwordx2 v[10:11], v[2:3], off
	v_lshl_add_u64 v[2:3], v[8:9], 0, s[10:11]
	s_or_b32 s10, s7, s9
	s_mulk_i32 s10, 0x410
	v_add_u32_e32 v44, s10, v43
	ds_read_b128 v[44:47], v44
	v_readlane_b32 s6, v41, s7
	v_readlane_b32 s8, v42, s7
	s_or_b32 s50, s50, 0x3800
	global_load_dwordx2 v[12:13], v[2:3], off
	s_waitcnt lgkmcnt(0)
	v_fma_f32 v44, -v0, s6, v44
	v_fma_f32 v45, -v35, s6, v45
	v_fma_f32 v46, -v37, s6, v46
	v_fma_f32 v47, -v39, s6, v47
	v_fma_f32 v44, s8, v44, v34
	v_fma_f32 v45, s8, v45, v36
	v_fma_f32 v46, s8, v46, v38
	v_fma_f32 v47, s8, v47, v40
	v_mul_f32_e32 v44, 0xbfb8aa3b, v44
	v_mul_f32_e32 v45, 0xbfb8aa3b, v45
	v_mul_f32_e32 v46, 0xbfb8aa3b, v46
	v_mul_f32_e32 v47, 0xbfb8aa3b, v47
	v_exp_f32_e32 v44, v44
	v_exp_f32_e32 v45, v45
	v_exp_f32_e32 v46, v46
	v_exp_f32_e32 v47, v47
	v_add_f32_e32 v44, 1.0, v44
	v_add_f32_e32 v45, 1.0, v45
	v_add_f32_e32 v46, 1.0, v46
	v_add_f32_e32 v47, 1.0, v47
	v_rcp_f32_e32 v44, v44
	v_rcp_f32_e32 v45, v45
	v_rcp_f32_e32 v46, v46
	v_rcp_f32_e32 v47, v47
	s_or_b32 s8, s7, 1
	s_or_b32 s12, s8, s9
	v_lshl_add_u64 v[2:3], v[6:7], 0, s[50:51]
	v_lshl_add_u64 v[4:5], v[8:9], 0, s[50:51]
	s_mulk_i32 s12, 0x410
	global_load_dwordx2 v[2:3], v[2:3], off
	v_readlane_b32 s10, v41, s8
	global_load_dwordx2 v[4:5], v[4:5], off
	v_readlane_b32 s11, v42, s8
	s_lshl_b32 s50, s8, 11
	s_or_b32 s8, s7, 2
	s_mov_b32 s6, 1
	s_and_b64 vcc, exec, s[4:5]
	s_mov_b64 s[4:5], 0
	s_waitcnt vmcnt(14)
	v_lshlrev_b32_e32 v56, 16, v52
	v_lshlrev_b32_e32 v54, 16, v48
	v_and_b32_e32 v55, 0xffff0000, v48
	v_and_b32_e32 v57, 0xffff0000, v52
	v_lshlrev_b32_e32 v48, 16, v49
	v_and_b32_e32 v49, 0xffff0000, v49
	v_lshlrev_b32_e32 v52, 16, v53
	v_and_b32_e32 v53, 0xffff0000, v53
	v_pk_fma_f32 v[44:45], v[44:45], v[54:55], v[56:57]
	v_pk_fma_f32 v[46:47], v[46:47], v[48:49], v[52:53]
	v_cvt_pk_bf16_f32 v44, v44, v45
	v_cvt_pk_bf16_f32 v45, v46, v47
	global_store_dwordx2 v[50:51], v[44:45], off
	v_add_u32_e32 v44, s12, v43
	ds_read_b128 v[44:47], v44
	s_waitcnt vmcnt(14)
	v_lshlrev_b32_e32 v48, 16, v32
	v_and_b32_e32 v49, 0xffff0000, v32
	s_waitcnt vmcnt(13)
	v_lshlrev_b32_e32 v50, 16, v30
	v_and_b32_e32 v51, 0xffff0000, v30
	s_waitcnt lgkmcnt(0)
	v_fma_f32 v44, -v0, s10, v44
	v_fma_f32 v45, -v35, s10, v45
	v_fma_f32 v46, -v37, s10, v46
	v_fma_f32 v47, -v39, s10, v47
	v_fma_f32 v44, s11, v44, v34
	v_fma_f32 v45, s11, v45, v36
	v_fma_f32 v46, s11, v46, v38
	v_fma_f32 v47, s11, v47, v40
	v_mul_f32_e32 v44, 0xbfb8aa3b, v44
	v_mul_f32_e32 v45, 0xbfb8aa3b, v45
	v_mul_f32_e32 v46, 0xbfb8aa3b, v46
	v_mul_f32_e32 v47, 0xbfb8aa3b, v47
	v_exp_f32_e32 v44, v44
	v_exp_f32_e32 v45, v45
	v_exp_f32_e32 v46, v46
	v_exp_f32_e32 v47, v47
	v_add_f32_e32 v44, 1.0, v44
	v_add_f32_e32 v45, 1.0, v45
	v_add_f32_e32 v46, 1.0, v46
	v_add_f32_e32 v47, 1.0, v47
	v_rcp_f32_e32 v44, v44
	v_rcp_f32_e32 v45, v45
	v_rcp_f32_e32 v46, v46
	v_rcp_f32_e32 v47, v47
	v_lshlrev_b32_e32 v32, 16, v33
	v_and_b32_e32 v33, 0xffff0000, v33
	v_lshlrev_b32_e32 v30, 16, v31
	v_and_b32_e32 v31, 0xffff0000, v31
	v_pk_fma_f32 v[44:45], v[44:45], v[48:49], v[50:51]
	v_pk_fma_f32 v[30:31], v[46:47], v[32:33], v[30:31]
	s_or_b32 s12, s8, s9
	v_cvt_pk_bf16_f32 v32, v44, v45
	v_cvt_pk_bf16_f32 v33, v30, v31
	v_lshl_add_u64 v[30:31], v[8:9], 0, s[50:51]
	s_mulk_i32 s12, 0x410
	global_store_dwordx2 v[30:31], v[32:33], off
	v_add_u32_e32 v30, s12, v43
	ds_read_b128 v[30:33], v30
	v_readlane_b32 s10, v41, s8
	v_readlane_b32 s11, v42, s8
	s_waitcnt vmcnt(13)
	v_lshlrev_b32_e32 v44, 16, v26
	v_and_b32_e32 v45, 0xffff0000, v26
	s_waitcnt lgkmcnt(0)
	v_fma_f32 v30, -v0, s10, v30
	v_fma_f32 v31, -v35, s10, v31
	v_fma_f32 v32, -v37, s10, v32
	v_fma_f32 v33, -v39, s10, v33
	v_fma_f32 v30, s11, v30, v34
	v_fma_f32 v31, s11, v31, v36
	v_fma_f32 v32, s11, v32, v38
	v_fma_f32 v33, s11, v33, v40
	v_mul_f32_e32 v30, 0xbfb8aa3b, v30
	v_mul_f32_e32 v31, 0xbfb8aa3b, v31
	v_mul_f32_e32 v32, 0xbfb8aa3b, v32
	v_mul_f32_e32 v33, 0xbfb8aa3b, v33
	v_exp_f32_e32 v30, v30
	v_exp_f32_e32 v31, v31
	v_exp_f32_e32 v32, v32
	v_exp_f32_e32 v33, v33
	v_add_f32_e32 v30, 1.0, v30
	v_add_f32_e32 v31, 1.0, v31
	v_add_f32_e32 v32, 1.0, v32
	v_add_f32_e32 v33, 1.0, v33
	v_rcp_f32_e32 v30, v30
	v_rcp_f32_e32 v31, v31
	v_rcp_f32_e32 v32, v32
	v_rcp_f32_e32 v33, v33
	s_waitcnt vmcnt(12)
; DI unsigned pack2(float a, float b) { fl2_t v = {a, b}; bf2_t r = __builtin_convertvector(v, bf2_t); return __builtin_bit_cast(unsigned, r); }
; DI float bflo(unsigned u) { return __uint_as_float(u << 16); }
; DI float bfhi(unsigned u) { return __uint_as_float(u & 0xffff0000u); }
; DI float sigmoidf_(float x) { return __builtin_amdgcn_rcpf(1.f + __builtin_amdgcn_exp2f(-1.4426950408889634f * x)); }
; DI float rl(float v, int srclane) { return __int_as_float(__builtin_amdgcn_readlane(__float_as_int(v), srclane)); }
; DI void epi_rows(const Params& p, int L, int ekind, const float* T, int rbase, int bcol) {
;     ...
;         for (int i = 0; i < 8; ++i) {
;           const int ri = ch * 8 + i;
;           const float mu = rl(rs_l.mu, ri), rstd = rl(rs_l.rstd, ri);
;           f32x4 t = *(const f32x4*)(T + (lr0 + ri) * TSTR + c4);
;           float sf[4] = {bflo(sv[i][0]), bfhi(sv[i][0]), bflo(sv[i][1]), bfhi(sv[i][1])};
;           float v[4];
;           for (int k = 0; k < 4; ++k) v[k] = sigmoidf_(rstd * (t[k] - mu * cs4[k]) + bw4[k]) * sf[k];
;           if (!a) { v[0] += bflo(mv[i][0]); v[1] += bfhi(mv[i][0]); v[2] += bflo(mv[i][1]); v[3] += bfhi(mv[i][1]); }
;           u32x2 o; o[0] = pack2(v[0], v[1]); o[1] = pack2(v[2], v[3]);
;           stg<u32x2>(Mx + (size_t)ri * 1024, o);
;         }
	v_lshlrev_b32_e32 v46, 16, v28
	v_and_b32_e32 v47, 0xffff0000, v28
	v_lshlrev_b32_e32 v26, 16, v27
	v_and_b32_e32 v27, 0xffff0000, v27
	v_lshlrev_b32_e32 v28, 16, v29
	v_and_b32_e32 v29, 0xffff0000, v29
	s_lshl_b32 s50, s8, 11
	s_or_b32 s8, s7, 3
	v_pk_fma_f32 v[30:31], v[30:31], v[44:45], v[46:47]
	v_pk_fma_f32 v[26:27], v[32:33], v[26:27], v[28:29]
	s_or_b32 s12, s8, s9
	v_cvt_pk_bf16_f32 v28, v30, v31
	v_cvt_pk_bf16_f32 v29, v26, v27
	v_lshl_add_u64 v[26:27], v[8:9], 0, s[50:51]
	s_mulk_i32 s12, 0x410
	global_store_dwordx2 v[26:27], v[28:29], off
	v_add_u32_e32 v26, s12, v43
	ds_read_b128 v[26:29], v26
	v_readlane_b32 s10, v41, s8
	v_readlane_b32 s11, v42, s8
	s_waitcnt vmcnt(12)
	v_lshlrev_b32_e32 v30, 16, v22
	v_and_b32_e32 v31, 0xffff0000, v22
	s_waitcnt lgkmcnt(0)
	v_fma_f32 v26, -v0, s10, v26
	v_fma_f32 v27, -v35, s10, v27
	v_fma_f32 v28, -v37, s10, v28
	v_fma_f32 v29, -v39, s10, v29
	v_fma_f32 v26, s11, v26, v34
	v_fma_f32 v27, s11, v27, v36
	v_fma_f32 v28, s11, v28, v38
	v_fma_f32 v29, s11, v29, v40
	v_mul_f32_e32 v26, 0xbfb8aa3b, v26
	v_mul_f32_e32 v27, 0xbfb8aa3b, v27
	v_mul_f32_e32 v28, 0xbfb8aa3b, v28
	v_mul_f32_e32 v29, 0xbfb8aa3b, v29
	v_exp_f32_e32 v26, v26
	v_exp_f32_e32 v27, v27
	v_exp_f32_e32 v28, v28
	v_exp_f32_e32 v29, v29
	v_add_f32_e32 v26, 1.0, v26
	v_add_f32_e32 v27, 1.0, v27
	v_add_f32_e32 v28, 1.0, v28
	v_add_f32_e32 v29, 1.0, v29
	v_rcp_f32_e32 v26, v26
	v_rcp_f32_e32 v27, v27
	v_rcp_f32_e32 v28, v28
	v_rcp_f32_e32 v29, v29
	s_waitcnt vmcnt(11)
	v_lshlrev_b32_e32 v32, 16, v24
	v_and_b32_e32 v33, 0xffff0000, v24
	v_lshlrev_b32_e32 v22, 16, v23
	v_and_b32_e32 v23, 0xffff0000, v23
	v_lshlrev_b32_e32 v24, 16, v25
	v_and_b32_e32 v25, 0xffff0000, v25
	s_lshl_b32 s50, s8, 11
	s_or_b32 s8, s7, 4
	v_pk_fma_f32 v[26:27], v[26:27], v[30:31], v[32:33]
	v_pk_fma_f32 v[22:23], v[28:29], v[22:23], v[24:25]
	s_or_b32 s12, s8, s9
	v_cvt_pk_bf16_f32 v24, v26, v27
	v_cvt_pk_bf16_f32 v25, v22, v23
	v_lshl_add_u64 v[22:23], v[8:9], 0, s[50:51]
	s_mulk_i32 s12, 0x410
	global_store_dwordx2 v[22:23], v[24:25], off
	v_add_u32_e32 v22, s12, v43
	ds_read_b128 v[22:25], v22
	v_readlane_b32 s10, v41, s8
	v_readlane_b32 s11, v42, s8
	s_waitcnt vmcnt(11)
	v_lshlrev_b32_e32 v26, 16, v18
	v_and_b32_e32 v27, 0xffff0000, v18
	s_waitcnt lgkmcnt(0)
	v_fma_f32 v22, -v0, s10, v22
	v_fma_f32 v23, -v35, s10, v23
	v_fma_f32 v24, -v37, s10, v24
	v_fma_f32 v25, -v39, s10, v25
	v_fma_f32 v22, s11, v22, v34
	v_fma_f32 v23, s11, v23, v36
	v_fma_f32 v24, s11, v24, v38
	v_fma_f32 v25, s11, v25, v40
	v_mul_f32_e32 v22, 0xbfb8aa3b, v22
	v_mul_f32_e32 v23, 0xbfb8aa3b, v23
	v_mul_f32_e32 v24, 0xbfb8aa3b, v24
	v_mul_f32_e32 v25, 0xbfb8aa3b, v25
	v_exp_f32_e32 v22, v22
	v_exp_f32_e32 v23, v23
	v_exp_f32_e32 v24, v24
	v_exp_f32_e32 v25, v25
	v_add_f32_e32 v22, 1.0, v22
	v_add_f32_e32 v23, 1.0, v23
	v_add_f32_e32 v24, 1.0, v24
	v_add_f32_e32 v25, 1.0, v25
	v_rcp_f32_e32 v22, v22
	v_rcp_f32_e32 v23, v23
	v_rcp_f32_e32 v24, v24
	v_rcp_f32_e32 v25, v25
	s_waitcnt vmcnt(10)
	v_lshlrev_b32_e32 v28, 16, v20
	v_and_b32_e32 v29, 0xffff0000, v20
	v_lshlrev_b32_e32 v18, 16, v19
	v_and_b32_e32 v19, 0xffff0000, v19
	v_lshlrev_b32_e32 v20, 16, v21
	v_and_b32_e32 v21, 0xffff0000, v21
	s_lshl_b32 s50, s8, 11
	s_or_b32 s8, s7, 5
	v_pk_fma_f32 v[22:23], v[22:23], v[26:27], v[28:29]
	v_pk_fma_f32 v[18:19], v[24:25], v[18:19], v[20:21]
	s_or_b32 s12, s8, s9
	v_cvt_pk_bf16_f32 v20, v22, v23
	v_cvt_pk_bf16_f32 v21, v18, v19
	v_lshl_add_u64 v[18:19], v[8:9], 0, s[50:51]
	s_mulk_i32 s12, 0x410
	global_store_dwordx2 v[18:19], v[20:21], off
	v_add_u32_e32 v18, s12, v43
	ds_read_b128 v[18:21], v18
	v_readlane_b32 s10, v41, s8
	v_readlane_b32 s11, v42, s8
	s_waitcnt vmcnt(10)
	v_lshlrev_b32_e32 v22, 16, v14
	v_and_b32_e32 v23, 0xffff0000, v14
	s_waitcnt lgkmcnt(0)
	v_fma_f32 v18, -v0, s10, v18
	v_fma_f32 v19, -v35, s10, v19
	v_fma_f32 v20, -v37, s10, v20
	v_fma_f32 v21, -v39, s10, v21
	v_fma_f32 v18, s11, v18, v34
	v_fma_f32 v19, s11, v19, v36
	v_fma_f32 v20, s11, v20, v38
	v_fma_f32 v21, s11, v21, v40
	v_mul_f32_e32 v18, 0xbfb8aa3b, v18
	v_mul_f32_e32 v19, 0xbfb8aa3b, v19
	v_mul_f32_e32 v20, 0xbfb8aa3b, v20
	v_mul_f32_e32 v21, 0xbfb8aa3b, v21
	v_exp_f32_e32 v18, v18
	v_exp_f32_e32 v19, v19
	v_exp_f32_e32 v20, v20
	v_exp_f32_e32 v21, v21
	v_add_f32_e32 v18, 1.0, v18
	v_add_f32_e32 v19, 1.0, v19
	v_add_f32_e32 v20, 1.0, v20
	v_add_f32_e32 v21, 1.0, v21
	v_rcp_f32_e32 v18, v18
	v_rcp_f32_e32 v19, v19
	v_rcp_f32_e32 v20, v20
	v_rcp_f32_e32 v21, v21
	s_waitcnt vmcnt(9)
	v_lshlrev_b32_e32 v24, 16, v16
	v_and_b32_e32 v25, 0xffff0000, v16
	v_lshlrev_b32_e32 v14, 16, v15
	v_and_b32_e32 v15, 0xffff0000, v15
	v_lshlrev_b32_e32 v16, 16, v17
	v_and_b32_e32 v17, 0xffff0000, v17
	s_lshl_b32 s50, s8, 11
	s_or_b32 s8, s7, 6
	v_pk_fma_f32 v[18:19], v[18:19], v[22:23], v[24:25]
	v_pk_fma_f32 v[14:15], v[20:21], v[14:15], v[16:17]
	s_or_b32 s12, s8, s9
	v_cvt_pk_bf16_f32 v16, v18, v19
	v_cvt_pk_bf16_f32 v17, v14, v15
	v_lshl_add_u64 v[14:15], v[8:9], 0, s[50:51]
	s_mulk_i32 s12, 0x410
	global_store_dwordx2 v[14:15], v[16:17], off
	v_add_u32_e32 v14, s12, v43
	ds_read_b128 v[14:17], v14
	v_readlane_b32 s10, v41, s8
	v_readlane_b32 s11, v42, s8
	s_waitcnt vmcnt(9)
	v_lshlrev_b32_e32 v18, 16, v10
	v_and_b32_e32 v19, 0xffff0000, v10
	s_waitcnt lgkmcnt(0)
; DI unsigned pack2(float a, float b) { fl2_t v = {a, b}; bf2_t r = __builtin_convertvector(v, bf2_t); return __builtin_bit_cast(unsigned, r); }
; DI float bflo(unsigned u) { return __uint_as_float(u << 16); }
; DI float bfhi(unsigned u) { return __uint_as_float(u & 0xffff0000u); }
; DI float sigmoidf_(float x) { return __builtin_amdgcn_rcpf(1.f + __builtin_amdgcn_exp2f(-1.4426950408889634f * x)); }
; DI float rl(float v, int srclane) { return __int_as_float(__builtin_amdgcn_readlane(__float_as_int(v), srclane)); }
; DI void epi_rows(const Params& p, int L, int ekind, const float* T, int rbase, int bcol) {
;     ...
;         for (int i = 0; i < 8; ++i) {
;           const int ri = ch * 8 + i;
;           const float mu = rl(rs_l.mu, ri), rstd = rl(rs_l.rstd, ri);
;           f32x4 t = *(const f32x4*)(T + (lr0 + ri) * TSTR + c4);
;           float sf[4] = {bflo(sv[i][0]), bfhi(sv[i][0]), bflo(sv[i][1]), bfhi(sv[i][1])};
;           float v[4];
;           for (int k = 0; k < 4; ++k) v[k] = sigmoidf_(rstd * (t[k] - mu * cs4[k]) + bw4[k]) * sf[k];
;           if (!a) { v[0] += bflo(mv[i][0]); v[1] += bfhi(mv[i][0]); v[2] += bflo(mv[i][1]); v[3] += bfhi(mv[i][1]); }
;           u32x2 o; o[0] = pack2(v[0], v[1]); o[1] = pack2(v[2], v[3]);
;           stg<u32x2>(Mx + (size_t)ri * 1024, o);
;         }
; __global__ void __launch_bounds__(NTHREADS) mega(Params p_) {
;     ...
;     GSYNC;
;     for (int rep = 0; rep < REP_G5; ++rep) g5_phase(p, L);
;     GSYNC;
;     gemm_phase_t<6, 0>(p, L); GSYNC;
	v_fma_f32 v14, -v0, s10, v14
	v_fma_f32 v15, -v35, s10, v15
	v_fma_f32 v16, -v37, s10, v16
	v_fma_f32 v17, -v39, s10, v17
	v_fma_f32 v14, s11, v14, v34
	v_fma_f32 v15, s11, v15, v36
	v_fma_f32 v16, s11, v16, v38
	v_fma_f32 v17, s11, v17, v40
	v_mul_f32_e32 v14, 0xbfb8aa3b, v14
	v_mul_f32_e32 v15, 0xbfb8aa3b, v15
	v_mul_f32_e32 v16, 0xbfb8aa3b, v16
	v_mul_f32_e32 v17, 0xbfb8aa3b, v17
	v_exp_f32_e32 v14, v14
	v_exp_f32_e32 v15, v15
	v_exp_f32_e32 v16, v16
	v_exp_f32_e32 v17, v17
	v_add_f32_e32 v14, 1.0, v14
	v_add_f32_e32 v15, 1.0, v15
	v_add_f32_e32 v16, 1.0, v16
	v_add_f32_e32 v17, 1.0, v17
	v_rcp_f32_e32 v14, v14
	v_rcp_f32_e32 v15, v15
	v_rcp_f32_e32 v16, v16
	v_rcp_f32_e32 v17, v17
	s_waitcnt vmcnt(8)
	v_lshlrev_b32_e32 v20, 16, v12
	v_and_b32_e32 v21, 0xffff0000, v12
	v_lshlrev_b32_e32 v10, 16, v11
	v_and_b32_e32 v11, 0xffff0000, v11
	v_lshlrev_b32_e32 v12, 16, v13
	v_and_b32_e32 v13, 0xffff0000, v13
	s_or_b32 s7, s7, 7
	v_pk_fma_f32 v[14:15], v[14:15], v[18:19], v[20:21]
	v_pk_fma_f32 v[10:11], v[16:17], v[10:11], v[12:13]
	s_lshl_b32 s50, s8, 11
	s_or_b32 s11, s7, s9
	v_cvt_pk_bf16_f32 v12, v14, v15
	v_cvt_pk_bf16_f32 v13, v10, v11
	v_lshl_add_u64 v[10:11], v[8:9], 0, s[50:51]
	s_mulk_i32 s11, 0x410
	global_store_dwordx2 v[10:11], v[12:13], off
	v_add_u32_e32 v10, s11, v43
	ds_read_b128 v[10:13], v10
	v_readlane_b32 s8, v41, s7
	v_readlane_b32 s10, v42, s7
	s_waitcnt vmcnt(8)
	v_lshlrev_b32_e32 v14, 16, v2
	v_and_b32_e32 v15, 0xffff0000, v2
	s_waitcnt lgkmcnt(0)
	v_fma_f32 v10, -v0, s8, v10
	v_fma_f32 v11, -v35, s8, v11
	v_fma_f32 v12, -v37, s8, v12
	v_fma_f32 v13, -v39, s8, v13
	v_fma_f32 v10, s10, v10, v34
	v_fma_f32 v11, s10, v11, v36
	v_fma_f32 v12, s10, v12, v38
	v_fma_f32 v13, s10, v13, v40
	v_mul_f32_e32 v10, 0xbfb8aa3b, v10
	v_mul_f32_e32 v11, 0xbfb8aa3b, v11
	v_mul_f32_e32 v12, 0xbfb8aa3b, v12
	v_mul_f32_e32 v13, 0xbfb8aa3b, v13
	v_exp_f32_e32 v10, v10
	v_exp_f32_e32 v11, v11
	v_exp_f32_e32 v12, v12
	v_exp_f32_e32 v13, v13
	v_add_f32_e32 v10, 1.0, v10
	v_add_f32_e32 v11, 1.0, v11
	v_add_f32_e32 v12, 1.0, v12
	v_add_f32_e32 v13, 1.0, v13
	v_rcp_f32_e32 v10, v10
	v_rcp_f32_e32 v11, v11
	v_rcp_f32_e32 v12, v12
	v_rcp_f32_e32 v13, v13
	s_waitcnt vmcnt(7)
	v_lshlrev_b32_e32 v16, 16, v4
	v_and_b32_e32 v17, 0xffff0000, v4
	v_lshlrev_b32_e32 v2, 16, v3
	v_and_b32_e32 v3, 0xffff0000, v3
	v_lshlrev_b32_e32 v4, 16, v5
	v_and_b32_e32 v5, 0xffff0000, v5
	v_pk_fma_f32 v[10:11], v[10:11], v[14:15], v[16:17]
	v_pk_fma_f32 v[2:3], v[12:13], v[2:3], v[4:5]
	s_lshl_b32 s50, s7, 11
	v_cvt_pk_bf16_f32 v4, v10, v11
	v_cvt_pk_bf16_f32 v5, v2, v3
	v_lshl_add_u64 v[2:3], v[8:9], 0, s[50:51]
	global_store_dwordx2 v[2:3], v[4:5], off
	s_cbranch_vccnz .LBB0_1767
	s_waitcnt vmcnt(0)
	s_barrier
	v_cmp_eq_u32_e32 vcc, 0, v178
	s_and_saveexec_b64 s[4:5], vcc
	s_cbranch_execz .Lg5pub_done
	buffer_wbl2 sc1
	s_waitcnt vmcnt(0)
	s_and_b32 s100, s62, 7
	s_mul_i32 s100, s100, 0x41
	s_lshr_b32 s101, s62, 3
	s_add_i32 s100, s100, s101
	s_lshr_b32 s101, s100, 4
	s_lshl_b32 s101, s101, 2
	s_and_b32 s100, s100, 15
	s_cmp_eq_u32 s101, 0x80
	s_cselect_b32 vcc_lo, 1, 3
	s_and_b32 s100, s100, vcc_lo
	s_add_i32 s100, s100, s101
	s_lshl_b32 s100, s100, 2
	s_add_u32 s100, s100, 0x405000
	v_readlane_b32 s101, v254, 27
	v_readlane_b32 vcc_lo, v254, 28
	s_nop 4
	s_add_u32 s100, s101, s100
	s_addc_u32 s101, vcc_lo, 0
	v_mov_b32_e32 v188, s100
	v_mov_b32_e32 v189, s101
	v_mov_b32_e32 v190, 1
	global_atomic_add v[188:189], v190, off sc1
.Lg5pub_done:
	s_or_b64 exec, exec, s[4:5]
	v_readlane_b32 s4, v254, 3
	s_add_i32 s62, s62, s4
	s_cmpk_lt_i32 s62, 0x208
	v_readlane_b32 s50, v254, 47
	v_readlane_b32 s5, v254, 4
	s_cbranch_scc1 .LBB0_1728
	v_readlane_b32 s68, v254, 25
	v_readlane_b32 s69, v254, 26
	v_readlane_b32 s70, v254, 27
	v_readlane_b32 s71, v254, 28
	s_mov_b32 s77, 0x2aaaaaab
	s_movk_i32 s66, 0x84
	s_movk_i32 s67, 0x1dff
	s_movk_i32 s76, 0x1e7f
.LBB0_1770:
	s_mov_b64 s[52:53], s[70:71]
	s_getreg_b32 s0, hwreg(HW_REG_XCC_ID, 0, 4)
	s_waitcnt vmcnt(0)
	s_barrier
	s_mov_b64 s[4:5], exec
	v_readlane_b32 s6, v254, 7
	v_readlane_b32 s7, v254, 8
	s_and_b64 s[6:7], s[4:5], s[6:7]
	s_xor_b64 s[36:37], s[6:7], s[4:5]
	s_mov_b64 exec, s[6:7]
	s_branch .LBB0_1815
	v_readlane_b32 s1, v254, 61
	s_waitcnt vmcnt(0) expcnt(0) lgkmcnt(0)
	s_and_b32 s50, s0, 15
	v_mov_b32_e32 v0, s1
	ds_read_b32 v2, v0
	v_readlane_b32 s1, v254, 62
	s_waitcnt lgkmcnt(0)
	v_cmp_ne_u32_e32 vcc, 0, v2
	v_mov_b32_e32 v0, s1
	ds_read_b32 v0, v0
	s_cbranch_vccnz .LBB0_1785
	s_add_u32 s0, s52, 0x404600
	s_addc_u32 s1, s53, 0
	s_add_u32 s6, s52, 0x404800
	s_addc_u32 s7, s53, 0
	s_add_u32 s8, s52, 0x404900
	s_addc_u32 s9, s53, 0
	s_add_u32 s10, s52, 0x404a00
	s_addc_u32 s11, s53, 0
	s_add_u32 s12, s52, 0x404b00
	s_addc_u32 s13, s53, 0
	s_add_u32 s14, s52, 0x404c00
	s_addc_u32 s15, s53, 0
	s_add_u32 s16, s52, 0x404d00
	s_addc_u32 s17, s53, 0
	s_add_u32 s18, s52, 0x404e00
	s_addc_u32 s19, s53, 0
	s_add_u32 s24, s52, 0x404f00
	s_addc_u32 s25, s53, 0
	s_add_u32 s26, s52, 0x405000
	s_addc_u32 s27, s53, 0
	s_add_u32 s28, s52, 0x405100
	s_addc_u32 s29, s53, 0
	s_add_u32 s30, s52, 0x405200
	s_addc_u32 s31, s53, 0
	s_add_u32 s34, s52, 0x405300
	v_writelane_b32 v255, s36, 16
	s_addc_u32 s35, s53, 0
	s_mov_b32 s85, 1
	v_writelane_b32 v255, s37, 17
	s_add_u32 s36, s52, 0x405400
	s_addc_u32 s37, s53, 0
	s_add_u32 s38, s52, 0x405500
	s_addc_u32 s39, s53, 0
	s_add_u32 s68, s52, 0x405600
	s_addc_u32 s69, s53, 0
	s_add_u32 s72, s52, 0x405700
	s_addc_u32 s73, s53, 0
	s_mov_b64 s[80:81], 0
	s_branch .LBB0_1775

;   #define STAGEA(P,br,kt) do{const u16* _gb=A+((long)(br)*LDA+(long)(kt)*BK); \
;     __builtin_amdgcn_global_load_lds((const unsigned*)(_gb+aoff0),(unsigned*)((char*)(P)+tidk*16),16,0,0); \
;     __builtin_amdgcn_global_load_lds((const unsigned*)(_gb+aoff1),(unsigned*)((char*)(P)+tidk*16+8192),16,0,0);}while(0)
;   #define STAGEB(P,br,kt) do{const u16* _gb=Bt+((long)(br)*K+(long)(kt)*BK); \
;     __builtin_amdgcn_global_load_lds((const unsigned*)(_gb+boff0),(unsigned*)((char*)(P)+tidk*16),16,0,0); \
;     __builtin_amdgcn_global_load_lds((const unsigned*)(_gb+boff1),(unsigned*)((char*)(P)+tidk*16+8192),16,0,0);}while(0)
;   #define BAR __builtin_amdgcn_s_barrier()
; template <int EK, int K, int LDA>
; DI void gemm_tile(const Params& p, int L, const u16* __restrict__ A, const u16* __restrict__ Bt, int pm, int pn) {
;     ...
;   const int brow = pm * BM, bcol = pn * BM;
;   const int wid = tidk >> 6, lane = tidk & 63, wr = wid >> 2, wc = wid & 3, fr = lane & 15, fq = lane >> 4;
;   unsigned aoff0, aoff1, boff0, boff1;
;   { int _r,_c; stage_rc(tidk*16,_r,_c); aoff0=(unsigned)(_r*LDA+_c); boff0=(unsigned)(_r*K+_c);
;     stage_rc(tidk*16+8192,_r,_c); aoff1=(unsigned)(_r*LDA+_c); boff1=(unsigned)(_r*K+_c); }
;   f32x4 acc[2][2][4][2] = {};
;   bf16x8 At[4][2], B0[2][2], B1[2][2];
;   constexpr int nt = K / BK;
;   STAGEB(SB(0,0),bcol,0); STAGEA(SA(0,0),brow,0);
;   STAGEB(SB(0,1),bcol+HALF,0); STAGEA(SA(0,1),brow+HALF,0);
;   if(wr==1)BAR;
.LBB0_1818:
	v_cmp_eq_u32_e32 vcc, 0, v178
	s_and_saveexec_b64 s[0:1], vcc
	s_cbranch_execz .Ls6acq_done
	s_and_b32 s100, s62, 7
	s_mul_i32 s100, s100, 0x41
	s_lshr_b32 s101, s62, 3
	s_add_i32 s100, s100, s101
	s_lshr_b32 s101, s100, 4
	s_lshl_b32 s101, s101, 2
	s_and_b32 s100, s100, 15
	s_cmp_eq_u32 s101, 0x80
	s_cselect_b32 vcc_lo, 1, 3
	s_and_b32 s100, s100, vcc_lo
	s_add_i32 s100, s100, s101
	s_lshl_b32 s100, s100, 2
	s_add_u32 s100, s100, 0x405000
	v_readlane_b32 s101, v254, 27
	v_readlane_b32 vcc_lo, v254, 28
	s_nop 4
	s_add_u32 s100, s101, s100
	s_addc_u32 s101, vcc_lo, 0
	v_mov_b32_e32 v188, s100
	v_mov_b32_e32 v189, s101
	v_readlane_b32 s100, v254, 48
	s_nop 3
	s_add_i32 s100, s100, 1
	s_lshl_b32 s100, s100, 2
	s_mov_b32 s101, 0
.Ls6poll:
	global_load_dword v190, v[188:189], off sc1
	s_waitcnt vmcnt(0)
	v_readfirstlane_b32 vcc_lo, v190
	s_nop 3
	s_cmp_ge_u32 vcc_lo, s100
	s_cbranch_scc1 .Ls6acq
	s_sleep 1
	s_add_u32 s101, s101, 1
	s_cmp_lt_u32 s101, 0x8000
	s_cbranch_scc1 .Ls6poll
.Ls6acq:
	buffer_inv sc1
	s_waitcnt vmcnt(0)
.Ls6acq_done:
	s_or_b64 exec, exec, s[0:1]
	s_barrier
	s_ashr_i32 s0, s62, 31
	s_lshr_b32 s0, s0, 29
	s_add_i32 s0, s62, s0
	s_ashr_i32 s1, s0, 3
	s_and_b32 s0, s0, -8
	s_sub_i32 s0, s62, s0
	s_cmp_lt_i32 s0, 0
	s_movk_i32 s4, 0x42
	s_cselect_b32 s6, s4, 0x41
	s_mul_i32 s14, s6, s0
	s_add_i32 s14, s14, s1
	s_ashr_i32 s0, s14, 31
	s_lshr_b32 s0, s0, 28
	s_add_i32 s0, s14, s0
	s_ashr_i32 s15, s0, 4
	s_lshl_b32 s6, s15, 2
	s_sub_i32 s1, 0x82, s6
	s_min_u32 s7, s1, 4
	s_and_b32 s0, s0, -16
	s_sub_i32 s8, s14, s0
	s_waitcnt vmcnt(0)
	v_cvt_f32_ubyte0_e32 v2, s7
	v_cvt_f32_i32_e32 v0, s8
	v_rcp_iflag_f32_e32 v3, v2
	s_ashr_i32 s0, s8, 30
	v_mov_b32_e32 v142, v178
	s_or_b32 s9, s0, 1
	v_mul_f32_e32 v3, v0, v3
	v_trunc_f32_e32 v3, v3
	v_fma_f32 v0, -v3, v2, v0
	v_cmp_ge_f32_e64 s[0:1], |v0|, v2
	v_cvt_i32_f32_e32 v3, v3
	v_ashrrev_i32_e32 v0, 31, v142
	v_lshrrev_b32_e32 v0, 26, v0
	v_add_u32_e32 v0, v142, v0
	v_ashrrev_i32_e32 v14, 6, v0
	v_bfe_i32 v0, v142, 27, 1
	v_lshlrev_b32_e32 v22, 4, v142
	v_lshrrev_b32_e32 v0, 22, v0
	v_add_u32_e32 v0, v22, v0
	v_and_b32_e32 v0, 0xfffffc00, v0
	v_sub_u32_e32 v0, v22, v0
	v_lshrrev_b32_e32 v2, 4, v0
	s_and_b64 s[0:1], s[0:1], exec
	v_bitop3_b32 v0, v2, v0, 32 bitop3:0x6c
	v_readfirstlane_b32 s1, v3
	v_ashrrev_i32_e32 v3, 31, v0
	v_lshrrev_b32_e32 v3, 26, v3
	v_lshlrev_b32_e32 v2, 3, v14
	v_add_u32_e32 v3, v0, v3
	v_and_b32_e32 v2, 0x3ffff0, v2
	v_ashrrev_i32_e32 v15, 6, v3
	v_lshlrev_b32_e32 v4, 5, v14
	v_and_b32_e32 v3, 0xc0, v3
	v_add_u32_e32 v2, v15, v2
	v_and_b32_e32 v16, 32, v4
	v_sub_u32_e32 v0, v0, v3
	v_ashrrev_i16_sdwa v17, v179, sext(v0) dst_sel:DWORD dst_unused:UNUSED_PAD src0_sel:DWORD src1_sel:BYTE_0
	v_lshl_or_b32 v0, v2, 10, v16
	v_add_u32_e32 v2, 0x2000, v22
	v_ashrrev_i32_e32 v3, 31, v2
	v_lshrrev_b32_e32 v3, 22, v3
	v_add_u32_e32 v3, v2, v3
	s_cselect_b32 s0, s9, 0
	v_ashrrev_i32_e32 v19, 10, v3
	s_add_i32 s16, s1, s0
	v_mul_i32_i24_e32 v3, 0x400, v19
	s_sext_i32_i8 s1, s16
	s_mul_i32 s16, s16, s7
	v_sub_u32_e32 v2, v2, v3
	s_sub_i32 s0, s8, s16
	v_lshrrev_b32_e32 v3, 4, v2
	s_sext_i32_i8 s0, s0
	v_bitop3_b32 v2, v3, v2, 32 bitop3:0x6c
	s_add_i32 s6, s6, s0
	v_ashrrev_i32_e32 v4, 31, v2
	s_lshl_b32 s0, s6, 8
	s_lshl_b32 s6, s1, 8
	v_lshrrev_b32_e32 v4, 26, v4
	v_lshlrev_b32_e32 v3, 3, v19
	v_add_u32_e32 v4, v2, v4
	s_ashr_i32 s7, s6, 31
	v_and_b32_e32 v3, 0x3ffff0, v3
	v_ashrrev_i32_e32 v20, 6, v4
	v_lshlrev_b32_e32 v5, 5, v19
	v_and_b32_e32 v4, 0xc0, v4
	s_lshl_b64 s[10:11], s[6:7], 11
	v_add_u32_sdwa v0, v0, sext(v17) dst_sel:DWORD dst_unused:UNUSED_PAD src0_sel:DWORD src1_sel:WORD_0
	v_add_u32_e32 v3, v20, v3
	v_and_b32_e32 v21, 32, v5
	v_sub_u32_e32 v2, v2, v4
	s_add_u32 s8, s38, s10
	v_add_u32_e32 v146, s3, v22
	v_ashrrev_i16_sdwa v23, v179, sext(v2) dst_sel:DWORD dst_unused:UNUSED_PAD src0_sel:DWORD src1_sel:BYTE_0
	v_lshl_or_b32 v2, v3, 10, v21
	s_addc_u32 s9, s39, s11
	v_lshlrev_b64 v[24:25], 1, v[0:1]
	v_readfirstlane_b32 s1, v146
	v_add_u32_e32 v147, 0x2000, v146
	v_add_u32_sdwa v4, v2, sext(v23) dst_sel:DWORD dst_unused:UNUSED_PAD src0_sel:DWORD src1_sel:WORD_0
	v_lshl_add_u64 v[2:3], s[8:9], 0, v[24:25]
	s_mov_b32 m0, s1
	v_mov_b32_e32 v5, v1
	v_readfirstlane_b32 s1, v147
	global_load_lds_dwordx4 v[2:3], off
	v_lshlrev_b64 v[26:27], 1, v[4:5]
	s_mov_b32 m0, s1
	s_ashr_i32 s1, s0, 31
	v_lshl_add_u64 v[4:5], s[8:9], 0, v[26:27]
	s_lshl_b64 s[8:9], s[0:1], 11
	s_add_u32 s8, s36, s8
	s_addc_u32 s9, s37, s9
	v_lshl_add_u64 v[6:7], s[8:9], 0, v[24:25]
	v_lshl_add_u64 v[8:9], s[8:9], 0, v[26:27]
	s_or_b32 s8, s6, 0x80
	s_ashr_i32 s9, s8, 31
	s_lshl_b64 s[8:9], s[8:9], 11
	s_add_u32 s8, s38, s8
	v_add_u32_e32 v148, 0, v22
	s_addc_u32 s9, s39, s9
	v_readfirstlane_b32 s1, v148
	v_add_u32_e32 v149, 0x2000, v148
	v_lshl_add_u64 v[12:13], s[8:9], 0, v[24:25]
	v_lshl_add_u64 v[10:11], s[8:9], 0, v[26:27]
	s_or_b32 s8, s0, 0x80
	global_load_lds_dwordx4 v[4:5], off
	s_mov_b32 m0, s1
	v_readfirstlane_b32 s1, v149
	v_add_u32_e32 v151, s50, v22
	s_ashr_i32 s9, s8, 31
	global_load_lds_dwordx4 v[6:7], off
	s_mov_b32 m0, s1
	v_readfirstlane_b32 s1, v151
	v_add_u32_e32 v152, 0x2000, v151
	s_lshl_b64 s[12:13], s[8:9], 11
	global_load_lds_dwordx4 v[8:9], off
	s_mov_b32 m0, s1
	v_readfirstlane_b32 s1, v152
	s_add_u32 s12, s36, s12
	v_add_u32_e32 v153, 0x4000, v148
	global_load_lds_dwordx4 v[12:13], off
	s_mov_b32 m0, s1
	s_addc_u32 s13, s37, s13
	v_readfirstlane_b32 s1, v153
	v_add_u32_e32 v155, 0x6000, v148
	global_load_lds_dwordx4 v[10:11], off
	v_lshl_add_u64 v[130:131], s[12:13], 0, v[24:25]
	s_mov_b32 m0, s1
	v_readfirstlane_b32 s1, v155
	global_load_lds_dwordx4 v[130:131], off
	v_lshl_add_u64 v[132:133], s[12:13], 0, v[26:27]
	s_mov_b32 m0, s1
	v_ashrrev_i32_e32 v18, 8, v142
	global_load_lds_dwordx4 v[132:133], off
	v_cmp_eq_u32_e32 vcc, 1, v18
	s_and_saveexec_b64 s[12:13], vcc
	s_cbranch_execz .LBB0_1820
	s_barrier
